# lever 2 (de-serialisation): hand-written oanorm loop keeps four iterations of loads in flight instead of load-then-wait per iteration
# speedup vs baseline: 1.0088x; 1.0008x over previous
.LBB0_667:
	s_or_b64 exec, exec, s[2:3]
	v_and_b32_e32 v16, 0x70, v156
	v_readlane_b32 s4, v236, 3
	v_lshlrev_b32_e32 v17, 2, v16
	v_readlane_b32 s16, v236, 15
	v_readlane_b32 s17, v236, 16
	s_barrier
	s_nop 3
	global_load_dwordx4 v[0:3], v17, s[16:17] offset:48
	global_load_dwordx4 v[4:7], v17, s[16:17] offset:32
	global_load_dwordx4 v[8:11], v17, s[16:17] offset:16
	global_load_dwordx4 v[12:15], v17, s[16:17]
	v_lshl_or_b32 v22, s65, 9, v145
	v_mov_b32_e32 v23, 0
	s_add_u32 s0, s66, s38
	v_or_b32_e32 v16, s1, v16
	v_lshlrev_b64 v[18:19], 14, v[22:23]
	s_addc_u32 s1, s67, s39
	v_xor_b32_e32 v17, 4, v165
	v_lshl_add_u64 v[18:19], s[0:1], 0, v[18:19]
	s_add_u32 s0, s50, s28
	v_cmp_lt_i32_e32 vcc, v17, v167
	v_lshlrev_b64 v[20:21], 12, v[22:23]
	s_addc_u32 s1, s51, s29
	v_cndmask_b32_e32 v17, v165, v17, vcc
	v_lshl_add_u64 v[20:21], s[0:1], 0, v[20:21]
	s_add_u32 s0, s48, s30
	v_readlane_b32 s5, v236, 4
	v_readlane_b32 s6, v236, 5
	v_readlane_b32 s7, v236, 6
	v_readlane_b32 s8, v236, 7
	v_readlane_b32 s9, v236, 8
	v_readlane_b32 s10, v236, 9
	v_readlane_b32 s11, v236, 10
	v_readlane_b32 s12, v236, 11
	v_readlane_b32 s13, v236, 12
	v_readlane_b32 s14, v236, 13
	v_readlane_b32 s15, v236, 14
	v_readlane_b32 s18, v236, 17
	v_lshlrev_b32_e32 v203, 2, v17
	v_mov_b32_e32 v17, v23
	v_lshlrev_b64 v[22:23], 11, v[22:23]
	s_addc_u32 s1, s49, s31
	v_lshlrev_b32_e32 v16, 1, v16
	v_lshl_add_u64 v[22:23], s[0:1], 0, v[22:23]
	s_mov_b32 s0, 8
	s_mov_b64 s[4:5], 0x1800
	s_movk_i32 s1, 0x1000
	v_mov_b32_e32 v30, 0x358637bd
	s_mov_b32 s16, 0x800000
	s_mov_b64 s[6:7], 0x20000
	s_mov_b32 s17, 0x20000
	s_mov_b64 s[8:9], 0x101800
	s_mov_b32 s18, 0x101000
	s_mov_b64 s[10:11], 0x200000
	s_mov_b64 s[12:13], 0x80000
	s_mov_b64 s[14:15], 0x40000
	v_readlane_b32 s19, v236, 18
	v_lshl_add_u64 v[24:25], v[22:23], 0, v[16:17]
	v_lshl_add_u64 v[26:27], v[18:19], 0, v[16:17]
	v_lshl_add_u64 v[26:27], v[26:27], 0, s[4:5]
	v_lshl_add_u64 v[28:29], v[20:21], 0, v[16:17]
	s_mov_b64 s[2:3], 0x100000
	global_load_dwordx4 v[52:55], v[24:25], off
	global_load_dwordx4 v[56:59], v[24:25], off offset:16
	global_load_dwordx4 v[60:63], v[26:27], off
	global_load_dwordx4 v[64:67], v[26:27], off offset:16
	v_lshl_add_u64 v[24:25], v[24:25], 0, s[6:7]
	v_lshl_add_u64 v[26:27], v[26:27], 0, s[2:3]
	global_load_dwordx4 v[68:71], v[24:25], off
	global_load_dwordx4 v[72:75], v[24:25], off offset:16
	global_load_dwordx4 v[76:79], v[26:27], off
	global_load_dwordx4 v[80:83], v[26:27], off offset:16
	v_lshl_add_u64 v[24:25], v[24:25], 0, s[6:7]
	v_lshl_add_u64 v[26:27], v[26:27], 0, s[2:3]
	global_load_dwordx4 v[84:87], v[24:25], off
	global_load_dwordx4 v[88:91], v[24:25], off offset:16
	global_load_dwordx4 v[92:95], v[26:27], off
	global_load_dwordx4 v[96:99], v[26:27], off offset:16
	v_lshl_add_u64 v[24:25], v[24:25], 0, s[6:7]
	v_lshl_add_u64 v[26:27], v[26:27], 0, s[2:3]
	global_load_dwordx4 v[100:103], v[24:25], off
	global_load_dwordx4 v[104:107], v[24:25], off offset:16
	global_load_dwordx4 v[108:111], v[26:27], off
	global_load_dwordx4 v[112:115], v[26:27], off offset:16
	v_lshl_add_u64 v[24:25], v[24:25], 0, s[6:7]
	v_lshl_add_u64 v[26:27], v[26:27], 0, s[2:3]
	s_waitcnt vmcnt(12)
	v_lshlrev_b32_e32 v116, 16, v52
	v_and_b32_e32 v117, 0xffff0000, v52
	v_lshlrev_b32_e32 v118, 16, v53
	v_and_b32_e32 v119, 0xffff0000, v53
	v_lshlrev_b32_e32 v120, 16, v54
	v_and_b32_e32 v121, 0xffff0000, v54
	v_lshlrev_b32_e32 v122, 16, v55
	v_and_b32_e32 v123, 0xffff0000, v55
	v_lshlrev_b32_e32 v124, 16, v56
	v_and_b32_e32 v125, 0xffff0000, v56
	v_lshlrev_b32_e32 v126, 16, v57
	v_and_b32_e32 v127, 0xffff0000, v57
	v_lshlrev_b32_e32 v128, 16, v58
	v_and_b32_e32 v129, 0xffff0000, v58
	v_lshlrev_b32_e32 v130, 16, v59
	v_and_b32_e32 v131, 0xffff0000, v59
	v_pk_mul_f32 v[136:137], v[116:117], v[116:117]
	s_nop 0
	v_add_f32_e32 v132, v136, v137
	v_pk_mul_f32 v[136:137], v[118:119], v[118:119]
	s_nop 0
	v_add_f32_e32 v132, v136, v132
	v_add_f32_e32 v132, v137, v132
	v_pk_mul_f32 v[136:137], v[120:121], v[120:121]
	s_nop 0
	v_add_f32_e32 v132, v136, v132
	v_add_f32_e32 v132, v137, v132
	v_pk_mul_f32 v[136:137], v[122:123], v[122:123]
	s_nop 0
	v_add_f32_e32 v132, v136, v132
	v_add_f32_e32 v132, v137, v132
	v_pk_mul_f32 v[136:137], v[124:125], v[124:125]
	s_nop 0
	v_add_f32_e32 v132, v136, v132
	v_add_f32_e32 v132, v137, v132
	v_pk_mul_f32 v[136:137], v[126:127], v[126:127]
	s_nop 0
	v_add_f32_e32 v132, v136, v132
	v_add_f32_e32 v132, v137, v132
	v_pk_mul_f32 v[136:137], v[128:129], v[128:129]
	s_nop 0
	v_add_f32_e32 v132, v136, v132
	v_add_f32_e32 v132, v137, v132
	v_pk_mul_f32 v[136:137], v[130:131], v[130:131]
	s_nop 0
	v_add_f32_e32 v132, v136, v132
	v_add_f32_e32 v132, v137, v132
	ds_bpermute_b32 v133, v199, v132
	s_waitcnt lgkmcnt(0)
	v_add_f32_e32 v132, v132, v133
	ds_bpermute_b32 v133, v200, v132
	s_waitcnt lgkmcnt(0)
	v_add_f32_e32 v132, v132, v133
	ds_bpermute_b32 v133, v203, v132
	s_waitcnt lgkmcnt(0)
	v_add_f32_e32 v132, v132, v133
	v_fmamk_f32 v132, v132, 0x3c000000, v30
	v_rsq_f32_e32 v134, v132
	s_nop 0
	v_pk_mul_f32 v[116:117], v[116:117], v[134:135] op_sel_hi:[1,0]
	v_pk_mul_f32 v[118:119], v[118:119], v[134:135] op_sel_hi:[1,0]
	v_pk_mul_f32 v[120:121], v[120:121], v[134:135] op_sel_hi:[1,0]
	v_pk_mul_f32 v[122:123], v[122:123], v[134:135] op_sel_hi:[1,0]
	v_pk_mul_f32 v[124:125], v[124:125], v[134:135] op_sel_hi:[1,0]
	v_pk_mul_f32 v[126:127], v[126:127], v[134:135] op_sel_hi:[1,0]
	v_pk_mul_f32 v[128:129], v[128:129], v[134:135] op_sel_hi:[1,0]
	v_pk_mul_f32 v[130:131], v[130:131], v[134:135] op_sel_hi:[1,0]
	v_pk_mul_f32 v[116:117], v[116:117], v[12:13]
	v_pk_mul_f32 v[118:119], v[118:119], v[14:15]
	v_pk_mul_f32 v[120:121], v[120:121], v[8:9]
	v_pk_mul_f32 v[122:123], v[122:123], v[10:11]
	v_pk_mul_f32 v[124:125], v[124:125], v[4:5]
	v_pk_mul_f32 v[126:127], v[126:127], v[6:7]
	v_pk_mul_f32 v[128:129], v[128:129], v[0:1]
	v_pk_mul_f32 v[130:131], v[130:131], v[2:3]
	v_lshlrev_b32_e32 v136, 16, v60
	v_and_b32_e32 v137, 0xffff0000, v60
	v_pk_mul_f32 v[116:117], v[116:117], v[136:137]
	s_nop 0
	v_cvt_pk_bf16_f32 v40, v116, v117
	v_lshlrev_b32_e32 v136, 16, v61
	v_and_b32_e32 v137, 0xffff0000, v61
	v_pk_mul_f32 v[118:119], v[118:119], v[136:137]
	s_nop 0
	v_cvt_pk_bf16_f32 v41, v118, v119
	v_lshlrev_b32_e32 v136, 16, v62
	v_and_b32_e32 v137, 0xffff0000, v62
	v_pk_mul_f32 v[120:121], v[120:121], v[136:137]
	s_nop 0
	v_cvt_pk_bf16_f32 v42, v120, v121
	v_lshlrev_b32_e32 v136, 16, v63
	v_and_b32_e32 v137, 0xffff0000, v63
	v_pk_mul_f32 v[122:123], v[122:123], v[136:137]
	s_nop 0
	v_cvt_pk_bf16_f32 v43, v122, v123
	v_lshlrev_b32_e32 v136, 16, v64
	v_and_b32_e32 v137, 0xffff0000, v64
	v_pk_mul_f32 v[124:125], v[124:125], v[136:137]
	s_nop 0
	v_cvt_pk_bf16_f32 v44, v124, v125
	v_lshlrev_b32_e32 v136, 16, v65
	v_and_b32_e32 v137, 0xffff0000, v65
	v_pk_mul_f32 v[126:127], v[126:127], v[136:137]
	s_nop 0
	v_cvt_pk_bf16_f32 v45, v126, v127
	v_lshlrev_b32_e32 v136, 16, v66
	v_and_b32_e32 v137, 0xffff0000, v66
	v_pk_mul_f32 v[128:129], v[128:129], v[136:137]
	s_nop 0
	v_cvt_pk_bf16_f32 v46, v128, v129
	v_lshlrev_b32_e32 v136, 16, v67
	v_and_b32_e32 v137, 0xffff0000, v67
	v_pk_mul_f32 v[130:131], v[130:131], v[136:137]
	s_nop 0
	v_cvt_pk_bf16_f32 v47, v130, v131
	global_store_dwordx4 v[28:29], v[40:43], off
	global_store_dwordx4 v[28:29], v[44:47], off offset:16
	v_lshl_add_u64 v[28:29], v[28:29], 0, s[14:15]
	global_load_dwordx4 v[52:55], v[24:25], off
	global_load_dwordx4 v[56:59], v[24:25], off offset:16
	global_load_dwordx4 v[60:63], v[26:27], off
	global_load_dwordx4 v[64:67], v[26:27], off offset:16
	v_lshl_add_u64 v[24:25], v[24:25], 0, s[6:7]
	v_lshl_add_u64 v[26:27], v[26:27], 0, s[2:3]
	s_waitcnt vmcnt(12)
	v_lshlrev_b32_e32 v116, 16, v68
	v_and_b32_e32 v117, 0xffff0000, v68
	v_lshlrev_b32_e32 v118, 16, v69
	v_and_b32_e32 v119, 0xffff0000, v69
	v_lshlrev_b32_e32 v120, 16, v70
	v_and_b32_e32 v121, 0xffff0000, v70
	v_lshlrev_b32_e32 v122, 16, v71
	v_and_b32_e32 v123, 0xffff0000, v71
	v_lshlrev_b32_e32 v124, 16, v72
	v_and_b32_e32 v125, 0xffff0000, v72
	v_lshlrev_b32_e32 v126, 16, v73
	v_and_b32_e32 v127, 0xffff0000, v73
	v_lshlrev_b32_e32 v128, 16, v74
	v_and_b32_e32 v129, 0xffff0000, v74
	v_lshlrev_b32_e32 v130, 16, v75
	v_and_b32_e32 v131, 0xffff0000, v75
	v_pk_mul_f32 v[136:137], v[116:117], v[116:117]
	s_nop 0
	v_add_f32_e32 v132, v136, v137
	v_pk_mul_f32 v[136:137], v[118:119], v[118:119]
	s_nop 0
	v_add_f32_e32 v132, v136, v132
	v_add_f32_e32 v132, v137, v132
	v_pk_mul_f32 v[136:137], v[120:121], v[120:121]
	s_nop 0
	v_add_f32_e32 v132, v136, v132
	v_add_f32_e32 v132, v137, v132
	v_pk_mul_f32 v[136:137], v[122:123], v[122:123]
	s_nop 0
	v_add_f32_e32 v132, v136, v132
	v_add_f32_e32 v132, v137, v132
	v_pk_mul_f32 v[136:137], v[124:125], v[124:125]
	s_nop 0
	v_add_f32_e32 v132, v136, v132
	v_add_f32_e32 v132, v137, v132
	v_pk_mul_f32 v[136:137], v[126:127], v[126:127]
	s_nop 0
	v_add_f32_e32 v132, v136, v132
	v_add_f32_e32 v132, v137, v132
	v_pk_mul_f32 v[136:137], v[128:129], v[128:129]
	s_nop 0
	v_add_f32_e32 v132, v136, v132
	v_add_f32_e32 v132, v137, v132
	v_pk_mul_f32 v[136:137], v[130:131], v[130:131]
	s_nop 0
	v_add_f32_e32 v132, v136, v132
	v_add_f32_e32 v132, v137, v132
	ds_bpermute_b32 v133, v199, v132
	s_waitcnt lgkmcnt(0)
	v_add_f32_e32 v132, v132, v133
	ds_bpermute_b32 v133, v200, v132
	s_waitcnt lgkmcnt(0)
	v_add_f32_e32 v132, v132, v133
	ds_bpermute_b32 v133, v203, v132
	s_waitcnt lgkmcnt(0)
	v_add_f32_e32 v132, v132, v133
	v_fmamk_f32 v132, v132, 0x3c000000, v30
	v_rsq_f32_e32 v134, v132
	s_nop 0
	v_pk_mul_f32 v[116:117], v[116:117], v[134:135] op_sel_hi:[1,0]
	v_pk_mul_f32 v[118:119], v[118:119], v[134:135] op_sel_hi:[1,0]
	v_pk_mul_f32 v[120:121], v[120:121], v[134:135] op_sel_hi:[1,0]
	v_pk_mul_f32 v[122:123], v[122:123], v[134:135] op_sel_hi:[1,0]
	v_pk_mul_f32 v[124:125], v[124:125], v[134:135] op_sel_hi:[1,0]
	v_pk_mul_f32 v[126:127], v[126:127], v[134:135] op_sel_hi:[1,0]
	v_pk_mul_f32 v[128:129], v[128:129], v[134:135] op_sel_hi:[1,0]
	v_pk_mul_f32 v[130:131], v[130:131], v[134:135] op_sel_hi:[1,0]
	v_pk_mul_f32 v[116:117], v[116:117], v[12:13]
	v_pk_mul_f32 v[118:119], v[118:119], v[14:15]
	v_pk_mul_f32 v[120:121], v[120:121], v[8:9]
	v_pk_mul_f32 v[122:123], v[122:123], v[10:11]
	v_pk_mul_f32 v[124:125], v[124:125], v[4:5]
	v_pk_mul_f32 v[126:127], v[126:127], v[6:7]
	v_pk_mul_f32 v[128:129], v[128:129], v[0:1]
	v_pk_mul_f32 v[130:131], v[130:131], v[2:3]
	v_lshlrev_b32_e32 v136, 16, v76
	v_and_b32_e32 v137, 0xffff0000, v76
	v_pk_mul_f32 v[116:117], v[116:117], v[136:137]
	s_nop 0
	v_cvt_pk_bf16_f32 v40, v116, v117
	v_lshlrev_b32_e32 v136, 16, v77
	v_and_b32_e32 v137, 0xffff0000, v77
	v_pk_mul_f32 v[118:119], v[118:119], v[136:137]
	s_nop 0
	v_cvt_pk_bf16_f32 v41, v118, v119
	v_lshlrev_b32_e32 v136, 16, v78
	v_and_b32_e32 v137, 0xffff0000, v78
	v_pk_mul_f32 v[120:121], v[120:121], v[136:137]
	s_nop 0
	v_cvt_pk_bf16_f32 v42, v120, v121
	v_lshlrev_b32_e32 v136, 16, v79
	v_and_b32_e32 v137, 0xffff0000, v79
	v_pk_mul_f32 v[122:123], v[122:123], v[136:137]
	s_nop 0
	v_cvt_pk_bf16_f32 v43, v122, v123
	v_lshlrev_b32_e32 v136, 16, v80
	v_and_b32_e32 v137, 0xffff0000, v80
	v_pk_mul_f32 v[124:125], v[124:125], v[136:137]
	s_nop 0
	v_cvt_pk_bf16_f32 v44, v124, v125
	v_lshlrev_b32_e32 v136, 16, v81
	v_and_b32_e32 v137, 0xffff0000, v81
	v_pk_mul_f32 v[126:127], v[126:127], v[136:137]
	s_nop 0
	v_cvt_pk_bf16_f32 v45, v126, v127
	v_lshlrev_b32_e32 v136, 16, v82
	v_and_b32_e32 v137, 0xffff0000, v82
	v_pk_mul_f32 v[128:129], v[128:129], v[136:137]
	s_nop 0
	v_cvt_pk_bf16_f32 v46, v128, v129
	v_lshlrev_b32_e32 v136, 16, v83
	v_and_b32_e32 v137, 0xffff0000, v83
	v_pk_mul_f32 v[130:131], v[130:131], v[136:137]
	s_nop 0
	v_cvt_pk_bf16_f32 v47, v130, v131
	global_store_dwordx4 v[28:29], v[40:43], off
	global_store_dwordx4 v[28:29], v[44:47], off offset:16
	v_lshl_add_u64 v[28:29], v[28:29], 0, s[14:15]
	global_load_dwordx4 v[68:71], v[24:25], off
	global_load_dwordx4 v[72:75], v[24:25], off offset:16
	global_load_dwordx4 v[76:79], v[26:27], off
	global_load_dwordx4 v[80:83], v[26:27], off offset:16
	v_lshl_add_u64 v[24:25], v[24:25], 0, s[6:7]
	v_lshl_add_u64 v[26:27], v[26:27], 0, s[2:3]
	s_waitcnt vmcnt(12)
	v_lshlrev_b32_e32 v116, 16, v84
	v_and_b32_e32 v117, 0xffff0000, v84
	v_lshlrev_b32_e32 v118, 16, v85
	v_and_b32_e32 v119, 0xffff0000, v85
	v_lshlrev_b32_e32 v120, 16, v86
	v_and_b32_e32 v121, 0xffff0000, v86
	v_lshlrev_b32_e32 v122, 16, v87
	v_and_b32_e32 v123, 0xffff0000, v87
	v_lshlrev_b32_e32 v124, 16, v88
	v_and_b32_e32 v125, 0xffff0000, v88
	v_lshlrev_b32_e32 v126, 16, v89
	v_and_b32_e32 v127, 0xffff0000, v89
	v_lshlrev_b32_e32 v128, 16, v90
	v_and_b32_e32 v129, 0xffff0000, v90
	v_lshlrev_b32_e32 v130, 16, v91
	v_and_b32_e32 v131, 0xffff0000, v91
	v_pk_mul_f32 v[136:137], v[116:117], v[116:117]
	s_nop 0
	v_add_f32_e32 v132, v136, v137
	v_pk_mul_f32 v[136:137], v[118:119], v[118:119]
	s_nop 0
	v_add_f32_e32 v132, v136, v132
	v_add_f32_e32 v132, v137, v132
	v_pk_mul_f32 v[136:137], v[120:121], v[120:121]
	s_nop 0
	v_add_f32_e32 v132, v136, v132
	v_add_f32_e32 v132, v137, v132
	v_pk_mul_f32 v[136:137], v[122:123], v[122:123]
	s_nop 0
	v_add_f32_e32 v132, v136, v132
	v_add_f32_e32 v132, v137, v132
	v_pk_mul_f32 v[136:137], v[124:125], v[124:125]
	s_nop 0
	v_add_f32_e32 v132, v136, v132
	v_add_f32_e32 v132, v137, v132
	v_pk_mul_f32 v[136:137], v[126:127], v[126:127]
	s_nop 0
	v_add_f32_e32 v132, v136, v132
	v_add_f32_e32 v132, v137, v132
	v_pk_mul_f32 v[136:137], v[128:129], v[128:129]
	s_nop 0
	v_add_f32_e32 v132, v136, v132
	v_add_f32_e32 v132, v137, v132
	v_pk_mul_f32 v[136:137], v[130:131], v[130:131]
	s_nop 0
	v_add_f32_e32 v132, v136, v132
	v_add_f32_e32 v132, v137, v132
	ds_bpermute_b32 v133, v199, v132
	s_waitcnt lgkmcnt(0)
	v_add_f32_e32 v132, v132, v133
	ds_bpermute_b32 v133, v200, v132
	s_waitcnt lgkmcnt(0)
	v_add_f32_e32 v132, v132, v133
	ds_bpermute_b32 v133, v203, v132
	s_waitcnt lgkmcnt(0)
	v_add_f32_e32 v132, v132, v133
	v_fmamk_f32 v132, v132, 0x3c000000, v30
	v_rsq_f32_e32 v134, v132
	s_nop 0
	v_pk_mul_f32 v[116:117], v[116:117], v[134:135] op_sel_hi:[1,0]
	v_pk_mul_f32 v[118:119], v[118:119], v[134:135] op_sel_hi:[1,0]
	v_pk_mul_f32 v[120:121], v[120:121], v[134:135] op_sel_hi:[1,0]
	v_pk_mul_f32 v[122:123], v[122:123], v[134:135] op_sel_hi:[1,0]
	v_pk_mul_f32 v[124:125], v[124:125], v[134:135] op_sel_hi:[1,0]
	v_pk_mul_f32 v[126:127], v[126:127], v[134:135] op_sel_hi:[1,0]
	v_pk_mul_f32 v[128:129], v[128:129], v[134:135] op_sel_hi:[1,0]
	v_pk_mul_f32 v[130:131], v[130:131], v[134:135] op_sel_hi:[1,0]
	v_pk_mul_f32 v[116:117], v[116:117], v[12:13]
	v_pk_mul_f32 v[118:119], v[118:119], v[14:15]
	v_pk_mul_f32 v[120:121], v[120:121], v[8:9]
	v_pk_mul_f32 v[122:123], v[122:123], v[10:11]
	v_pk_mul_f32 v[124:125], v[124:125], v[4:5]
	v_pk_mul_f32 v[126:127], v[126:127], v[6:7]
	v_pk_mul_f32 v[128:129], v[128:129], v[0:1]
	v_pk_mul_f32 v[130:131], v[130:131], v[2:3]
	v_lshlrev_b32_e32 v136, 16, v92
	v_and_b32_e32 v137, 0xffff0000, v92
	v_pk_mul_f32 v[116:117], v[116:117], v[136:137]
	s_nop 0
	v_cvt_pk_bf16_f32 v40, v116, v117
	v_lshlrev_b32_e32 v136, 16, v93
	v_and_b32_e32 v137, 0xffff0000, v93
	v_pk_mul_f32 v[118:119], v[118:119], v[136:137]
	s_nop 0
	v_cvt_pk_bf16_f32 v41, v118, v119
	v_lshlrev_b32_e32 v136, 16, v94
	v_and_b32_e32 v137, 0xffff0000, v94
	v_pk_mul_f32 v[120:121], v[120:121], v[136:137]
	s_nop 0
	v_cvt_pk_bf16_f32 v42, v120, v121
	v_lshlrev_b32_e32 v136, 16, v95
	v_and_b32_e32 v137, 0xffff0000, v95
	v_pk_mul_f32 v[122:123], v[122:123], v[136:137]
	s_nop 0
	v_cvt_pk_bf16_f32 v43, v122, v123
	v_lshlrev_b32_e32 v136, 16, v96
	v_and_b32_e32 v137, 0xffff0000, v96
	v_pk_mul_f32 v[124:125], v[124:125], v[136:137]
	s_nop 0
	v_cvt_pk_bf16_f32 v44, v124, v125
	v_lshlrev_b32_e32 v136, 16, v97
	v_and_b32_e32 v137, 0xffff0000, v97
	v_pk_mul_f32 v[126:127], v[126:127], v[136:137]
	s_nop 0
	v_cvt_pk_bf16_f32 v45, v126, v127
	v_lshlrev_b32_e32 v136, 16, v98
	v_and_b32_e32 v137, 0xffff0000, v98
	v_pk_mul_f32 v[128:129], v[128:129], v[136:137]
	s_nop 0
	v_cvt_pk_bf16_f32 v46, v128, v129
	v_lshlrev_b32_e32 v136, 16, v99
	v_and_b32_e32 v137, 0xffff0000, v99
	v_pk_mul_f32 v[130:131], v[130:131], v[136:137]
	s_nop 0
	v_cvt_pk_bf16_f32 v47, v130, v131
	global_store_dwordx4 v[28:29], v[40:43], off
	global_store_dwordx4 v[28:29], v[44:47], off offset:16
	v_lshl_add_u64 v[28:29], v[28:29], 0, s[14:15]
	global_load_dwordx4 v[84:87], v[24:25], off
	global_load_dwordx4 v[88:91], v[24:25], off offset:16
	global_load_dwordx4 v[92:95], v[26:27], off
	global_load_dwordx4 v[96:99], v[26:27], off offset:16
	v_lshl_add_u64 v[24:25], v[24:25], 0, s[6:7]
	v_lshl_add_u64 v[26:27], v[26:27], 0, s[2:3]
	s_waitcnt vmcnt(12)
	v_lshlrev_b32_e32 v116, 16, v100
	v_and_b32_e32 v117, 0xffff0000, v100
	v_lshlrev_b32_e32 v118, 16, v101
	v_and_b32_e32 v119, 0xffff0000, v101
	v_lshlrev_b32_e32 v120, 16, v102
	v_and_b32_e32 v121, 0xffff0000, v102
	v_lshlrev_b32_e32 v122, 16, v103
	v_and_b32_e32 v123, 0xffff0000, v103
	v_lshlrev_b32_e32 v124, 16, v104
	v_and_b32_e32 v125, 0xffff0000, v104
	v_lshlrev_b32_e32 v126, 16, v105
	v_and_b32_e32 v127, 0xffff0000, v105
	v_lshlrev_b32_e32 v128, 16, v106
	v_and_b32_e32 v129, 0xffff0000, v106
	v_lshlrev_b32_e32 v130, 16, v107
	v_and_b32_e32 v131, 0xffff0000, v107
	v_pk_mul_f32 v[136:137], v[116:117], v[116:117]
	s_nop 0
	v_add_f32_e32 v132, v136, v137
	v_pk_mul_f32 v[136:137], v[118:119], v[118:119]
	s_nop 0
	v_add_f32_e32 v132, v136, v132
	v_add_f32_e32 v132, v137, v132
	v_pk_mul_f32 v[136:137], v[120:121], v[120:121]
	s_nop 0
	v_add_f32_e32 v132, v136, v132
	v_add_f32_e32 v132, v137, v132
	v_pk_mul_f32 v[136:137], v[122:123], v[122:123]
	s_nop 0
	v_add_f32_e32 v132, v136, v132
	v_add_f32_e32 v132, v137, v132
	v_pk_mul_f32 v[136:137], v[124:125], v[124:125]
	s_nop 0
	v_add_f32_e32 v132, v136, v132
	v_add_f32_e32 v132, v137, v132
	v_pk_mul_f32 v[136:137], v[126:127], v[126:127]
	s_nop 0
	v_add_f32_e32 v132, v136, v132
	v_add_f32_e32 v132, v137, v132
	v_pk_mul_f32 v[136:137], v[128:129], v[128:129]
	s_nop 0
	v_add_f32_e32 v132, v136, v132
	v_add_f32_e32 v132, v137, v132
	v_pk_mul_f32 v[136:137], v[130:131], v[130:131]
	s_nop 0
	v_add_f32_e32 v132, v136, v132
	v_add_f32_e32 v132, v137, v132
	ds_bpermute_b32 v133, v199, v132
	s_waitcnt lgkmcnt(0)
	v_add_f32_e32 v132, v132, v133
	ds_bpermute_b32 v133, v200, v132
	s_waitcnt lgkmcnt(0)
	v_add_f32_e32 v132, v132, v133
	ds_bpermute_b32 v133, v203, v132
	s_waitcnt lgkmcnt(0)
	v_add_f32_e32 v132, v132, v133
	v_fmamk_f32 v132, v132, 0x3c000000, v30
	v_rsq_f32_e32 v134, v132
	s_nop 0
	v_pk_mul_f32 v[116:117], v[116:117], v[134:135] op_sel_hi:[1,0]
	v_pk_mul_f32 v[118:119], v[118:119], v[134:135] op_sel_hi:[1,0]
	v_pk_mul_f32 v[120:121], v[120:121], v[134:135] op_sel_hi:[1,0]
	v_pk_mul_f32 v[122:123], v[122:123], v[134:135] op_sel_hi:[1,0]
	v_pk_mul_f32 v[124:125], v[124:125], v[134:135] op_sel_hi:[1,0]
	v_pk_mul_f32 v[126:127], v[126:127], v[134:135] op_sel_hi:[1,0]
	v_pk_mul_f32 v[128:129], v[128:129], v[134:135] op_sel_hi:[1,0]
	v_pk_mul_f32 v[130:131], v[130:131], v[134:135] op_sel_hi:[1,0]
	v_pk_mul_f32 v[116:117], v[116:117], v[12:13]
	v_pk_mul_f32 v[118:119], v[118:119], v[14:15]
	v_pk_mul_f32 v[120:121], v[120:121], v[8:9]
	v_pk_mul_f32 v[122:123], v[122:123], v[10:11]
	v_pk_mul_f32 v[124:125], v[124:125], v[4:5]
	v_pk_mul_f32 v[126:127], v[126:127], v[6:7]
	v_pk_mul_f32 v[128:129], v[128:129], v[0:1]
	v_pk_mul_f32 v[130:131], v[130:131], v[2:3]
	v_lshlrev_b32_e32 v136, 16, v108
	v_and_b32_e32 v137, 0xffff0000, v108
	v_pk_mul_f32 v[116:117], v[116:117], v[136:137]
	s_nop 0
	v_cvt_pk_bf16_f32 v40, v116, v117
	v_lshlrev_b32_e32 v136, 16, v109
	v_and_b32_e32 v137, 0xffff0000, v109
	v_pk_mul_f32 v[118:119], v[118:119], v[136:137]
	s_nop 0
	v_cvt_pk_bf16_f32 v41, v118, v119
	v_lshlrev_b32_e32 v136, 16, v110
	v_and_b32_e32 v137, 0xffff0000, v110
	v_pk_mul_f32 v[120:121], v[120:121], v[136:137]
	s_nop 0
	v_cvt_pk_bf16_f32 v42, v120, v121
	v_lshlrev_b32_e32 v136, 16, v111
	v_and_b32_e32 v137, 0xffff0000, v111
	v_pk_mul_f32 v[122:123], v[122:123], v[136:137]
	s_nop 0
	v_cvt_pk_bf16_f32 v43, v122, v123
	v_lshlrev_b32_e32 v136, 16, v112
	v_and_b32_e32 v137, 0xffff0000, v112
	v_pk_mul_f32 v[124:125], v[124:125], v[136:137]
	s_nop 0
	v_cvt_pk_bf16_f32 v44, v124, v125
	v_lshlrev_b32_e32 v136, 16, v113
	v_and_b32_e32 v137, 0xffff0000, v113
	v_pk_mul_f32 v[126:127], v[126:127], v[136:137]
	s_nop 0
	v_cvt_pk_bf16_f32 v45, v126, v127
	v_lshlrev_b32_e32 v136, 16, v114
	v_and_b32_e32 v137, 0xffff0000, v114
	v_pk_mul_f32 v[128:129], v[128:129], v[136:137]
	s_nop 0
	v_cvt_pk_bf16_f32 v46, v128, v129
	v_lshlrev_b32_e32 v136, 16, v115
	v_and_b32_e32 v137, 0xffff0000, v115
	v_pk_mul_f32 v[130:131], v[130:131], v[136:137]
	s_nop 0
	v_cvt_pk_bf16_f32 v47, v130, v131
	global_store_dwordx4 v[28:29], v[40:43], off
	global_store_dwordx4 v[28:29], v[44:47], off offset:16
	v_lshl_add_u64 v[28:29], v[28:29], 0, s[14:15]
	global_load_dwordx4 v[100:103], v[24:25], off
	global_load_dwordx4 v[104:107], v[24:25], off offset:16
	global_load_dwordx4 v[108:111], v[26:27], off
	global_load_dwordx4 v[112:115], v[26:27], off offset:16
	v_lshl_add_u64 v[24:25], v[24:25], 0, s[6:7]
	v_lshl_add_u64 v[26:27], v[26:27], 0, s[2:3]
	s_waitcnt vmcnt(12)
	v_lshlrev_b32_e32 v116, 16, v52
	v_and_b32_e32 v117, 0xffff0000, v52
	v_lshlrev_b32_e32 v118, 16, v53
	v_and_b32_e32 v119, 0xffff0000, v53
	v_lshlrev_b32_e32 v120, 16, v54
	v_and_b32_e32 v121, 0xffff0000, v54
	v_lshlrev_b32_e32 v122, 16, v55
	v_and_b32_e32 v123, 0xffff0000, v55
	v_lshlrev_b32_e32 v124, 16, v56
	v_and_b32_e32 v125, 0xffff0000, v56
	v_lshlrev_b32_e32 v126, 16, v57
	v_and_b32_e32 v127, 0xffff0000, v57
	v_lshlrev_b32_e32 v128, 16, v58
	v_and_b32_e32 v129, 0xffff0000, v58
	v_lshlrev_b32_e32 v130, 16, v59
	v_and_b32_e32 v131, 0xffff0000, v59
	v_pk_mul_f32 v[136:137], v[116:117], v[116:117]
	s_nop 0
	v_add_f32_e32 v132, v136, v137
	v_pk_mul_f32 v[136:137], v[118:119], v[118:119]
	s_nop 0
	v_add_f32_e32 v132, v136, v132
	v_add_f32_e32 v132, v137, v132
	v_pk_mul_f32 v[136:137], v[120:121], v[120:121]
	s_nop 0
	v_add_f32_e32 v132, v136, v132
	v_add_f32_e32 v132, v137, v132
	v_pk_mul_f32 v[136:137], v[122:123], v[122:123]
	s_nop 0
	v_add_f32_e32 v132, v136, v132
	v_add_f32_e32 v132, v137, v132
	v_pk_mul_f32 v[136:137], v[124:125], v[124:125]
	s_nop 0
	v_add_f32_e32 v132, v136, v132
	v_add_f32_e32 v132, v137, v132
	v_pk_mul_f32 v[136:137], v[126:127], v[126:127]
	s_nop 0
	v_add_f32_e32 v132, v136, v132
	v_add_f32_e32 v132, v137, v132
	v_pk_mul_f32 v[136:137], v[128:129], v[128:129]
	s_nop 0
	v_add_f32_e32 v132, v136, v132
	v_add_f32_e32 v132, v137, v132
	v_pk_mul_f32 v[136:137], v[130:131], v[130:131]
	s_nop 0
	v_add_f32_e32 v132, v136, v132
	v_add_f32_e32 v132, v137, v132
	ds_bpermute_b32 v133, v199, v132
	s_waitcnt lgkmcnt(0)
	v_add_f32_e32 v132, v132, v133
	ds_bpermute_b32 v133, v200, v132
	s_waitcnt lgkmcnt(0)
	v_add_f32_e32 v132, v132, v133
	ds_bpermute_b32 v133, v203, v132
	s_waitcnt lgkmcnt(0)
	v_add_f32_e32 v132, v132, v133
	v_fmamk_f32 v132, v132, 0x3c000000, v30
	v_rsq_f32_e32 v134, v132
	s_nop 0
	v_pk_mul_f32 v[116:117], v[116:117], v[134:135] op_sel_hi:[1,0]
	v_pk_mul_f32 v[118:119], v[118:119], v[134:135] op_sel_hi:[1,0]
	v_pk_mul_f32 v[120:121], v[120:121], v[134:135] op_sel_hi:[1,0]
	v_pk_mul_f32 v[122:123], v[122:123], v[134:135] op_sel_hi:[1,0]
	v_pk_mul_f32 v[124:125], v[124:125], v[134:135] op_sel_hi:[1,0]
	v_pk_mul_f32 v[126:127], v[126:127], v[134:135] op_sel_hi:[1,0]
	v_pk_mul_f32 v[128:129], v[128:129], v[134:135] op_sel_hi:[1,0]
	v_pk_mul_f32 v[130:131], v[130:131], v[134:135] op_sel_hi:[1,0]
	v_pk_mul_f32 v[116:117], v[116:117], v[12:13]
	v_pk_mul_f32 v[118:119], v[118:119], v[14:15]
	v_pk_mul_f32 v[120:121], v[120:121], v[8:9]
	v_pk_mul_f32 v[122:123], v[122:123], v[10:11]
	v_pk_mul_f32 v[124:125], v[124:125], v[4:5]
	v_pk_mul_f32 v[126:127], v[126:127], v[6:7]
	v_pk_mul_f32 v[128:129], v[128:129], v[0:1]
	v_pk_mul_f32 v[130:131], v[130:131], v[2:3]
	v_lshlrev_b32_e32 v136, 16, v60
	v_and_b32_e32 v137, 0xffff0000, v60
	v_pk_mul_f32 v[116:117], v[116:117], v[136:137]
	s_nop 0
	v_cvt_pk_bf16_f32 v40, v116, v117
	v_lshlrev_b32_e32 v136, 16, v61
	v_and_b32_e32 v137, 0xffff0000, v61
	v_pk_mul_f32 v[118:119], v[118:119], v[136:137]
	s_nop 0
	v_cvt_pk_bf16_f32 v41, v118, v119
	v_lshlrev_b32_e32 v136, 16, v62
	v_and_b32_e32 v137, 0xffff0000, v62
	v_pk_mul_f32 v[120:121], v[120:121], v[136:137]
	s_nop 0
	v_cvt_pk_bf16_f32 v42, v120, v121
	v_lshlrev_b32_e32 v136, 16, v63
	v_and_b32_e32 v137, 0xffff0000, v63
	v_pk_mul_f32 v[122:123], v[122:123], v[136:137]
	s_nop 0
	v_cvt_pk_bf16_f32 v43, v122, v123
	v_lshlrev_b32_e32 v136, 16, v64
	v_and_b32_e32 v137, 0xffff0000, v64
	v_pk_mul_f32 v[124:125], v[124:125], v[136:137]
	s_nop 0
	v_cvt_pk_bf16_f32 v44, v124, v125
	v_lshlrev_b32_e32 v136, 16, v65
	v_and_b32_e32 v137, 0xffff0000, v65
	v_pk_mul_f32 v[126:127], v[126:127], v[136:137]
	s_nop 0
	v_cvt_pk_bf16_f32 v45, v126, v127
	v_lshlrev_b32_e32 v136, 16, v66
	v_and_b32_e32 v137, 0xffff0000, v66
	v_pk_mul_f32 v[128:129], v[128:129], v[136:137]
	s_nop 0
	v_cvt_pk_bf16_f32 v46, v128, v129
	v_lshlrev_b32_e32 v136, 16, v67
	v_and_b32_e32 v137, 0xffff0000, v67
	v_pk_mul_f32 v[130:131], v[130:131], v[136:137]
	s_nop 0
	v_cvt_pk_bf16_f32 v47, v130, v131
	global_store_dwordx4 v[28:29], v[40:43], off
	global_store_dwordx4 v[28:29], v[44:47], off offset:16
	v_lshl_add_u64 v[28:29], v[28:29], 0, s[14:15]
	s_waitcnt vmcnt(8)
	v_lshlrev_b32_e32 v116, 16, v68
	v_and_b32_e32 v117, 0xffff0000, v68
	v_lshlrev_b32_e32 v118, 16, v69
	v_and_b32_e32 v119, 0xffff0000, v69
	v_lshlrev_b32_e32 v120, 16, v70
	v_and_b32_e32 v121, 0xffff0000, v70
	v_lshlrev_b32_e32 v122, 16, v71
	v_and_b32_e32 v123, 0xffff0000, v71
	v_lshlrev_b32_e32 v124, 16, v72
	v_and_b32_e32 v125, 0xffff0000, v72
	v_lshlrev_b32_e32 v126, 16, v73
	v_and_b32_e32 v127, 0xffff0000, v73
	v_lshlrev_b32_e32 v128, 16, v74
	v_and_b32_e32 v129, 0xffff0000, v74
	v_lshlrev_b32_e32 v130, 16, v75
	v_and_b32_e32 v131, 0xffff0000, v75
	v_pk_mul_f32 v[136:137], v[116:117], v[116:117]
	s_nop 0
	v_add_f32_e32 v132, v136, v137
	v_pk_mul_f32 v[136:137], v[118:119], v[118:119]
	s_nop 0
	v_add_f32_e32 v132, v136, v132
	v_add_f32_e32 v132, v137, v132
	v_pk_mul_f32 v[136:137], v[120:121], v[120:121]
	s_nop 0
	v_add_f32_e32 v132, v136, v132
	v_add_f32_e32 v132, v137, v132
	v_pk_mul_f32 v[136:137], v[122:123], v[122:123]
	s_nop 0
	v_add_f32_e32 v132, v136, v132
	v_add_f32_e32 v132, v137, v132
	v_pk_mul_f32 v[136:137], v[124:125], v[124:125]
	s_nop 0
	v_add_f32_e32 v132, v136, v132
	v_add_f32_e32 v132, v137, v132
	v_pk_mul_f32 v[136:137], v[126:127], v[126:127]
	s_nop 0
	v_add_f32_e32 v132, v136, v132
	v_add_f32_e32 v132, v137, v132
	v_pk_mul_f32 v[136:137], v[128:129], v[128:129]
	s_nop 0
	v_add_f32_e32 v132, v136, v132
	v_add_f32_e32 v132, v137, v132
	v_pk_mul_f32 v[136:137], v[130:131], v[130:131]
	s_nop 0
	v_add_f32_e32 v132, v136, v132
	v_add_f32_e32 v132, v137, v132
	ds_bpermute_b32 v133, v199, v132
	s_waitcnt lgkmcnt(0)
	v_add_f32_e32 v132, v132, v133
	ds_bpermute_b32 v133, v200, v132
	s_waitcnt lgkmcnt(0)
	v_add_f32_e32 v132, v132, v133
	ds_bpermute_b32 v133, v203, v132
	s_waitcnt lgkmcnt(0)
	v_add_f32_e32 v132, v132, v133
	v_fmamk_f32 v132, v132, 0x3c000000, v30
	v_rsq_f32_e32 v134, v132
	s_nop 0
	v_pk_mul_f32 v[116:117], v[116:117], v[134:135] op_sel_hi:[1,0]
	v_pk_mul_f32 v[118:119], v[118:119], v[134:135] op_sel_hi:[1,0]
	v_pk_mul_f32 v[120:121], v[120:121], v[134:135] op_sel_hi:[1,0]
	v_pk_mul_f32 v[122:123], v[122:123], v[134:135] op_sel_hi:[1,0]
	v_pk_mul_f32 v[124:125], v[124:125], v[134:135] op_sel_hi:[1,0]
	v_pk_mul_f32 v[126:127], v[126:127], v[134:135] op_sel_hi:[1,0]
	v_pk_mul_f32 v[128:129], v[128:129], v[134:135] op_sel_hi:[1,0]
	v_pk_mul_f32 v[130:131], v[130:131], v[134:135] op_sel_hi:[1,0]
	v_pk_mul_f32 v[116:117], v[116:117], v[12:13]
	v_pk_mul_f32 v[118:119], v[118:119], v[14:15]
	v_pk_mul_f32 v[120:121], v[120:121], v[8:9]
	v_pk_mul_f32 v[122:123], v[122:123], v[10:11]
	v_pk_mul_f32 v[124:125], v[124:125], v[4:5]
	v_pk_mul_f32 v[126:127], v[126:127], v[6:7]
	v_pk_mul_f32 v[128:129], v[128:129], v[0:1]
	v_pk_mul_f32 v[130:131], v[130:131], v[2:3]
	v_lshlrev_b32_e32 v136, 16, v76
	v_and_b32_e32 v137, 0xffff0000, v76
	v_pk_mul_f32 v[116:117], v[116:117], v[136:137]
	s_nop 0
	v_cvt_pk_bf16_f32 v40, v116, v117
	v_lshlrev_b32_e32 v136, 16, v77
	v_and_b32_e32 v137, 0xffff0000, v77
	v_pk_mul_f32 v[118:119], v[118:119], v[136:137]
	s_nop 0
	v_cvt_pk_bf16_f32 v41, v118, v119
	v_lshlrev_b32_e32 v136, 16, v78
	v_and_b32_e32 v137, 0xffff0000, v78
	v_pk_mul_f32 v[120:121], v[120:121], v[136:137]
	s_nop 0
	v_cvt_pk_bf16_f32 v42, v120, v121
	v_lshlrev_b32_e32 v136, 16, v79
	v_and_b32_e32 v137, 0xffff0000, v79
	v_pk_mul_f32 v[122:123], v[122:123], v[136:137]
	s_nop 0
	v_cvt_pk_bf16_f32 v43, v122, v123
	v_lshlrev_b32_e32 v136, 16, v80
	v_and_b32_e32 v137, 0xffff0000, v80
	v_pk_mul_f32 v[124:125], v[124:125], v[136:137]
	s_nop 0
	v_cvt_pk_bf16_f32 v44, v124, v125
	v_lshlrev_b32_e32 v136, 16, v81
	v_and_b32_e32 v137, 0xffff0000, v81
	v_pk_mul_f32 v[126:127], v[126:127], v[136:137]
	s_nop 0
	v_cvt_pk_bf16_f32 v45, v126, v127
	v_lshlrev_b32_e32 v136, 16, v82
	v_and_b32_e32 v137, 0xffff0000, v82
	v_pk_mul_f32 v[128:129], v[128:129], v[136:137]
	s_nop 0
	v_cvt_pk_bf16_f32 v46, v128, v129
	v_lshlrev_b32_e32 v136, 16, v83
	v_and_b32_e32 v137, 0xffff0000, v83
	v_pk_mul_f32 v[130:131], v[130:131], v[136:137]
	s_nop 0
	v_cvt_pk_bf16_f32 v47, v130, v131
	global_store_dwordx4 v[28:29], v[40:43], off
	global_store_dwordx4 v[28:29], v[44:47], off offset:16
	v_lshl_add_u64 v[28:29], v[28:29], 0, s[14:15]
	s_waitcnt vmcnt(4)
	v_lshlrev_b32_e32 v116, 16, v84
	v_and_b32_e32 v117, 0xffff0000, v84
	v_lshlrev_b32_e32 v118, 16, v85
	v_and_b32_e32 v119, 0xffff0000, v85
	v_lshlrev_b32_e32 v120, 16, v86
	v_and_b32_e32 v121, 0xffff0000, v86
	v_lshlrev_b32_e32 v122, 16, v87
	v_and_b32_e32 v123, 0xffff0000, v87
	v_lshlrev_b32_e32 v124, 16, v88
	v_and_b32_e32 v125, 0xffff0000, v88
	v_lshlrev_b32_e32 v126, 16, v89
	v_and_b32_e32 v127, 0xffff0000, v89
	v_lshlrev_b32_e32 v128, 16, v90
	v_and_b32_e32 v129, 0xffff0000, v90
	v_lshlrev_b32_e32 v130, 16, v91
	v_and_b32_e32 v131, 0xffff0000, v91
	v_pk_mul_f32 v[136:137], v[116:117], v[116:117]
	s_nop 0
	v_add_f32_e32 v132, v136, v137
	v_pk_mul_f32 v[136:137], v[118:119], v[118:119]
	s_nop 0
	v_add_f32_e32 v132, v136, v132
	v_add_f32_e32 v132, v137, v132
	v_pk_mul_f32 v[136:137], v[120:121], v[120:121]
	s_nop 0
	v_add_f32_e32 v132, v136, v132
	v_add_f32_e32 v132, v137, v132
	v_pk_mul_f32 v[136:137], v[122:123], v[122:123]
	s_nop 0
	v_add_f32_e32 v132, v136, v132
	v_add_f32_e32 v132, v137, v132
	v_pk_mul_f32 v[136:137], v[124:125], v[124:125]
	s_nop 0
	v_add_f32_e32 v132, v136, v132
	v_add_f32_e32 v132, v137, v132
	v_pk_mul_f32 v[136:137], v[126:127], v[126:127]
	s_nop 0
	v_add_f32_e32 v132, v136, v132
	v_add_f32_e32 v132, v137, v132
	v_pk_mul_f32 v[136:137], v[128:129], v[128:129]
	s_nop 0
	v_add_f32_e32 v132, v136, v132
	v_add_f32_e32 v132, v137, v132
	v_pk_mul_f32 v[136:137], v[130:131], v[130:131]
	s_nop 0
	v_add_f32_e32 v132, v136, v132
	v_add_f32_e32 v132, v137, v132
	ds_bpermute_b32 v133, v199, v132
	s_waitcnt lgkmcnt(0)
	v_add_f32_e32 v132, v132, v133
	ds_bpermute_b32 v133, v200, v132
	s_waitcnt lgkmcnt(0)
	v_add_f32_e32 v132, v132, v133
	ds_bpermute_b32 v133, v203, v132
	s_waitcnt lgkmcnt(0)
	v_add_f32_e32 v132, v132, v133
	v_fmamk_f32 v132, v132, 0x3c000000, v30
	v_rsq_f32_e32 v134, v132
	s_nop 0
	v_pk_mul_f32 v[116:117], v[116:117], v[134:135] op_sel_hi:[1,0]
	v_pk_mul_f32 v[118:119], v[118:119], v[134:135] op_sel_hi:[1,0]
	v_pk_mul_f32 v[120:121], v[120:121], v[134:135] op_sel_hi:[1,0]
	v_pk_mul_f32 v[122:123], v[122:123], v[134:135] op_sel_hi:[1,0]
	v_pk_mul_f32 v[124:125], v[124:125], v[134:135] op_sel_hi:[1,0]
	v_pk_mul_f32 v[126:127], v[126:127], v[134:135] op_sel_hi:[1,0]
	v_pk_mul_f32 v[128:129], v[128:129], v[134:135] op_sel_hi:[1,0]
	v_pk_mul_f32 v[130:131], v[130:131], v[134:135] op_sel_hi:[1,0]
	v_pk_mul_f32 v[116:117], v[116:117], v[12:13]
	v_pk_mul_f32 v[118:119], v[118:119], v[14:15]
	v_pk_mul_f32 v[120:121], v[120:121], v[8:9]
	v_pk_mul_f32 v[122:123], v[122:123], v[10:11]
	v_pk_mul_f32 v[124:125], v[124:125], v[4:5]
	v_pk_mul_f32 v[126:127], v[126:127], v[6:7]
	v_pk_mul_f32 v[128:129], v[128:129], v[0:1]
	v_pk_mul_f32 v[130:131], v[130:131], v[2:3]
	v_lshlrev_b32_e32 v136, 16, v92
	v_and_b32_e32 v137, 0xffff0000, v92
	v_pk_mul_f32 v[116:117], v[116:117], v[136:137]
	s_nop 0
	v_cvt_pk_bf16_f32 v40, v116, v117
	v_lshlrev_b32_e32 v136, 16, v93
	v_and_b32_e32 v137, 0xffff0000, v93
	v_pk_mul_f32 v[118:119], v[118:119], v[136:137]
	s_nop 0
	v_cvt_pk_bf16_f32 v41, v118, v119
	v_lshlrev_b32_e32 v136, 16, v94
	v_and_b32_e32 v137, 0xffff0000, v94
	v_pk_mul_f32 v[120:121], v[120:121], v[136:137]
	s_nop 0
	v_cvt_pk_bf16_f32 v42, v120, v121
	v_lshlrev_b32_e32 v136, 16, v95
	v_and_b32_e32 v137, 0xffff0000, v95
	v_pk_mul_f32 v[122:123], v[122:123], v[136:137]
	s_nop 0
	v_cvt_pk_bf16_f32 v43, v122, v123
	v_lshlrev_b32_e32 v136, 16, v96
	v_and_b32_e32 v137, 0xffff0000, v96
	v_pk_mul_f32 v[124:125], v[124:125], v[136:137]
	s_nop 0
	v_cvt_pk_bf16_f32 v44, v124, v125
	v_lshlrev_b32_e32 v136, 16, v97
	v_and_b32_e32 v137, 0xffff0000, v97
	v_pk_mul_f32 v[126:127], v[126:127], v[136:137]
	s_nop 0
	v_cvt_pk_bf16_f32 v45, v126, v127
	v_lshlrev_b32_e32 v136, 16, v98
	v_and_b32_e32 v137, 0xffff0000, v98
	v_pk_mul_f32 v[128:129], v[128:129], v[136:137]
	s_nop 0
	v_cvt_pk_bf16_f32 v46, v128, v129
	v_lshlrev_b32_e32 v136, 16, v99
	v_and_b32_e32 v137, 0xffff0000, v99
	v_pk_mul_f32 v[130:131], v[130:131], v[136:137]
	s_nop 0
	v_cvt_pk_bf16_f32 v47, v130, v131
	global_store_dwordx4 v[28:29], v[40:43], off
	global_store_dwordx4 v[28:29], v[44:47], off offset:16
	v_lshl_add_u64 v[28:29], v[28:29], 0, s[14:15]
	s_waitcnt vmcnt(0)
	v_lshlrev_b32_e32 v116, 16, v100
	v_and_b32_e32 v117, 0xffff0000, v100
	v_lshlrev_b32_e32 v118, 16, v101
	v_and_b32_e32 v119, 0xffff0000, v101
	v_lshlrev_b32_e32 v120, 16, v102
	v_and_b32_e32 v121, 0xffff0000, v102
	v_lshlrev_b32_e32 v122, 16, v103
	v_and_b32_e32 v123, 0xffff0000, v103
	v_lshlrev_b32_e32 v124, 16, v104
	v_and_b32_e32 v125, 0xffff0000, v104
	v_lshlrev_b32_e32 v126, 16, v105
	v_and_b32_e32 v127, 0xffff0000, v105
	v_lshlrev_b32_e32 v128, 16, v106
	v_and_b32_e32 v129, 0xffff0000, v106
	v_lshlrev_b32_e32 v130, 16, v107
	v_and_b32_e32 v131, 0xffff0000, v107
	v_pk_mul_f32 v[136:137], v[116:117], v[116:117]
	s_nop 0
	v_add_f32_e32 v132, v136, v137
	v_pk_mul_f32 v[136:137], v[118:119], v[118:119]
	s_nop 0
	v_add_f32_e32 v132, v136, v132
	v_add_f32_e32 v132, v137, v132
	v_pk_mul_f32 v[136:137], v[120:121], v[120:121]
	s_nop 0
	v_add_f32_e32 v132, v136, v132
	v_add_f32_e32 v132, v137, v132
	v_pk_mul_f32 v[136:137], v[122:123], v[122:123]
	s_nop 0
	v_add_f32_e32 v132, v136, v132
	v_add_f32_e32 v132, v137, v132
	v_pk_mul_f32 v[136:137], v[124:125], v[124:125]
	s_nop 0
	v_add_f32_e32 v132, v136, v132
	v_add_f32_e32 v132, v137, v132
	v_pk_mul_f32 v[136:137], v[126:127], v[126:127]
	s_nop 0
	v_add_f32_e32 v132, v136, v132
	v_add_f32_e32 v132, v137, v132
	v_pk_mul_f32 v[136:137], v[128:129], v[128:129]
	s_nop 0
	v_add_f32_e32 v132, v136, v132
	v_add_f32_e32 v132, v137, v132
	v_pk_mul_f32 v[136:137], v[130:131], v[130:131]
	s_nop 0
	v_add_f32_e32 v132, v136, v132
	v_add_f32_e32 v132, v137, v132
	ds_bpermute_b32 v133, v199, v132
	s_waitcnt lgkmcnt(0)
	v_add_f32_e32 v132, v132, v133
	ds_bpermute_b32 v133, v200, v132
	s_waitcnt lgkmcnt(0)
	v_add_f32_e32 v132, v132, v133
	ds_bpermute_b32 v133, v203, v132
	s_waitcnt lgkmcnt(0)
	v_add_f32_e32 v132, v132, v133
	v_fmamk_f32 v132, v132, 0x3c000000, v30
	v_rsq_f32_e32 v134, v132
	s_nop 0
	v_pk_mul_f32 v[116:117], v[116:117], v[134:135] op_sel_hi:[1,0]
	v_pk_mul_f32 v[118:119], v[118:119], v[134:135] op_sel_hi:[1,0]
	v_pk_mul_f32 v[120:121], v[120:121], v[134:135] op_sel_hi:[1,0]
	v_pk_mul_f32 v[122:123], v[122:123], v[134:135] op_sel_hi:[1,0]
	v_pk_mul_f32 v[124:125], v[124:125], v[134:135] op_sel_hi:[1,0]
	v_pk_mul_f32 v[126:127], v[126:127], v[134:135] op_sel_hi:[1,0]
	v_pk_mul_f32 v[128:129], v[128:129], v[134:135] op_sel_hi:[1,0]
	v_pk_mul_f32 v[130:131], v[130:131], v[134:135] op_sel_hi:[1,0]
	v_pk_mul_f32 v[116:117], v[116:117], v[12:13]
	v_pk_mul_f32 v[118:119], v[118:119], v[14:15]
	v_pk_mul_f32 v[120:121], v[120:121], v[8:9]
	v_pk_mul_f32 v[122:123], v[122:123], v[10:11]
	v_pk_mul_f32 v[124:125], v[124:125], v[4:5]
	v_pk_mul_f32 v[126:127], v[126:127], v[6:7]
	v_pk_mul_f32 v[128:129], v[128:129], v[0:1]
	v_pk_mul_f32 v[130:131], v[130:131], v[2:3]
	v_lshlrev_b32_e32 v136, 16, v108
	v_and_b32_e32 v137, 0xffff0000, v108
	v_pk_mul_f32 v[116:117], v[116:117], v[136:137]
	s_nop 0
	v_cvt_pk_bf16_f32 v40, v116, v117
	v_lshlrev_b32_e32 v136, 16, v109
	v_and_b32_e32 v137, 0xffff0000, v109
	v_pk_mul_f32 v[118:119], v[118:119], v[136:137]
	s_nop 0
	v_cvt_pk_bf16_f32 v41, v118, v119
	v_lshlrev_b32_e32 v136, 16, v110
	v_and_b32_e32 v137, 0xffff0000, v110
	v_pk_mul_f32 v[120:121], v[120:121], v[136:137]
	s_nop 0
	v_cvt_pk_bf16_f32 v42, v120, v121
	v_lshlrev_b32_e32 v136, 16, v111
	v_and_b32_e32 v137, 0xffff0000, v111
	v_pk_mul_f32 v[122:123], v[122:123], v[136:137]
	s_nop 0
	v_cvt_pk_bf16_f32 v43, v122, v123
	v_lshlrev_b32_e32 v136, 16, v112
	v_and_b32_e32 v137, 0xffff0000, v112
	v_pk_mul_f32 v[124:125], v[124:125], v[136:137]
	s_nop 0
	v_cvt_pk_bf16_f32 v44, v124, v125
	v_lshlrev_b32_e32 v136, 16, v113
	v_and_b32_e32 v137, 0xffff0000, v113
	v_pk_mul_f32 v[126:127], v[126:127], v[136:137]
	s_nop 0
	v_cvt_pk_bf16_f32 v45, v126, v127
	v_lshlrev_b32_e32 v136, 16, v114
	v_and_b32_e32 v137, 0xffff0000, v114
	v_pk_mul_f32 v[128:129], v[128:129], v[136:137]
	s_nop 0
	v_cvt_pk_bf16_f32 v46, v128, v129
	v_lshlrev_b32_e32 v136, 16, v115
	v_and_b32_e32 v137, 0xffff0000, v115
	v_pk_mul_f32 v[130:131], v[130:131], v[136:137]
	s_nop 0
	v_cvt_pk_bf16_f32 v47, v130, v131
	global_store_dwordx4 v[28:29], v[40:43], off
	global_store_dwordx4 v[28:29], v[44:47], off offset:16
	v_lshl_add_u64 v[28:29], v[28:29], 0, s[14:15]
	s_mov_b32 s0, 0


	s_waitcnt vmcnt(0)
	s_barrier
	s_mov_b64 s[2:3], exec
	v_readlane_b32 s0, v236, 19
	v_readlane_b32 s1, v236, 20
	s_and_b64 s[0:1], s[2:3], s[0:1]
	s_mov_b64 exec, s[0:1]
	s_cbranch_execz .LBB0_721
	s_add_i32 s0, 0, 0x26000
	v_mov_b32_e32 v0, s0
	s_waitcnt vmcnt(0) expcnt(0) lgkmcnt(0)
	ds_read_b32 v2, v0
	s_add_i32 s0, 0, 0x26004
	v_mov_b32_e32 v0, s0
	ds_read_b32 v0, v0
	s_waitcnt lgkmcnt(1)
	v_cmp_ne_u32_e32 vcc, 0, v2
	s_cbranch_vccnz .LBB0_685
	s_add_u32 s4, s80, 0x8200
	s_addc_u32 s5, s81, 0
	s_add_u32 s6, s80, 0x8400
	s_addc_u32 s7, s81, 0
	s_add_u32 s8, s80, 0x8500
	s_addc_u32 s9, s81, 0
	s_add_u32 s10, s80, 0x8600
	s_addc_u32 s11, s81, 0
	s_add_u32 s12, s80, 0x8700
	s_addc_u32 s13, s81, 0
	s_add_u32 s14, s80, 0x8800
	s_addc_u32 s15, s81, 0
	s_add_u32 s16, s80, 0x8900
	s_addc_u32 s17, s81, 0
	s_add_u32 s18, s80, 0x8a00
	s_addc_u32 s19, s81, 0
	s_add_u32 s20, s80, 0x8b00
	s_addc_u32 s21, s81, 0
	s_add_u32 s22, s80, 0x8c00
	s_addc_u32 s23, s81, 0
	s_add_u32 s24, s80, 0x8d00
	s_addc_u32 s25, s81, 0
	s_add_u32 s26, s80, 0x8e00
	s_addc_u32 s27, s81, 0
	s_add_u32 s28, s80, 0x8f00
	s_addc_u32 s29, s81, 0
	s_add_u32 s30, s80, 0x9000
	s_addc_u32 s31, s81, 0
	s_add_u32 s34, s80, 0x9100
	s_addc_u32 s35, s81, 0
	s_add_u32 s36, s80, 0x9200
	v_readlane_b32 s0, v236, 2
	s_addc_u32 s37, s81, 0
	s_mul_i32 s0, s89, s0
	s_add_u32 s38, s80, 0x9300
	s_mul_i32 s0, s0, s88
	s_addc_u32 s39, s81, 0
	s_mov_b32 s1, 1
	v_mov_b32_e32 v16, 0
	s_branch .LBB0_673
